# S5 setup: 32 serialized C-matrix loads and 3 parameter loads issued as one batch
# speedup vs baseline: 1.0147x; 1.0001x over previous
; __device__ __forceinline__ void sincos_acc(float angf, float& s, float& c) {
;     const double x = (double)angf; const double k = rint(x * 0.15915494309189535); const double r = fma(-k, 6.283185307179586, x);
;     const double r2 = r * r; double ts = r, tc = 1.0, ss = r, cc = 1.0;
; #pragma unroll
;     for (int n = 1; n <= 14; ++n) { tc *= -r2 * (1.0 / (double)((2 * n - 1) * (2 * n))); cc += tc; ts *= -r2 * (1.0 / (double)((2 * n) * (2 * n + 1))); ss += ts; }
; __device__ __forceinline__ void s5_unit(LAS unsigned char* lw, int b, int g, const float* lam_re, const float* lam_im, const float* log_step, ...
;     ...
;     const float step = expf(log_step[g]); const float lr = fminf(lam_re[g * 64 + n], -1e-4f), li = lam_im[g * 64 + n];
;     const float mag = expf(lr * step); float sn, cs; sincos_acc(li * step, sn, cs);
.LBB0_727:
	s_and_b32 s26, s1, 31
	s_lshl_b32 s18, s26, 2
	v_mov_b32_e32 v2, s18
	global_load_dword v2, v2, s[12:13]
	s_mov_b32 s19, 0x3fb8aa3b
	s_mov_b32 s20, 0xc2ce8ed0
	s_mov_b32 s21, 0x42b17218
	s_lshl_b32 s18, s26, 6
	v_or_b32_e32 v208, s18, v67
	v_lshlrev_b32_e32 v208, 2, v208
	global_load_dword v209, v208, s[8:9]
	global_load_dword v208, v208, s[10:11]
	s_waitcnt vmcnt(0)
	v_mul_f32_e32 v3, 0x3fb8aa3b, v2
	v_fma_f32 v4, v2, s19, -v3
	v_rndne_f32_e32 v5, v3
	v_fmac_f32_e32 v4, 0x32a5705f, v2
	v_sub_f32_e32 v3, v3, v5
	v_add_f32_e32 v3, v3, v4
	v_exp_f32_e32 v3, v3
	v_cvt_i32_f32_e32 v4, v5
	v_cmp_ngt_f32_e32 vcc, s20, v2
	v_ldexp_f32 v3, v3, v4
	s_nop 0
	v_cndmask_b32_e32 v3, 0, v3, vcc
	v_cmp_nlt_f32_e32 vcc, s21, v2
	v_or_b32_e32 v2, s18, v67
	s_nop 0
	v_cndmask_b32_e32 v5, v222, v3, vcc
	v_lshlrev_b32_e32 v3, 2, v2
	v_mov_b32_e32 v2, v209
	v_max_f32_e32 v2, v2, v2
	v_mov_b32_e32 v3, v208
	v_min_f32_e32 v2, 0xb8d1b717, v2
	v_mul_f32_e32 v4, v5, v2
	v_mul_f32_e32 v6, 0x3fb8aa3b, v4
	v_fma_f32 v7, v4, s19, -v6
	v_rndne_f32_e32 v8, v6
	v_fmac_f32_e32 v7, 0x32a5705f, v4
	v_sub_f32_e32 v6, v6, v8
	v_add_f32_e32 v6, v6, v7
	v_exp_f32_e32 v6, v6
	v_cvt_i32_f32_e32 v7, v8
	v_cmp_ngt_f32_e32 vcc, s20, v4
	v_ldexp_f32 v6, v6, v7
	s_nop 0
	v_cndmask_b32_e32 v6, 0, v6, vcc
	v_cmp_nlt_f32_e32 vcc, s21, v4
	v_readlane_b32 s20, v255, 14
	v_readlane_b32 s21, v255, 15
	v_cndmask_b32_e32 v4, v222, v6, vcc
	s_mov_b32 s20, s40
	s_mov_b32 s19, s21
	v_writelane_b32 v255, s18, 14
	s_waitcnt vmcnt(0)
	v_mul_f32_e32 v5, v5, v3
	v_cvt_f64_f32_e32 v[6:7], v5
	v_mul_f64 v[8:9], v[6:7], s[30:31]
	v_rndne_f64_e32 v[8:9], v[8:9]
	v_fmac_f64_e32 v[6:7], s[36:37], v[8:9]
	v_mul_f64 v[10:11], v[6:7], -v[6:7]
	v_mul_f64 v[14:15], v[10:11], s[40:41]
	v_mul_f64 v[12:13], v[10:11], 0.5
	v_fma_f64 v[8:9], v[10:11], 0.5, 1.0
	v_mul_f64 v[16:17], v[6:7], v[14:15]
	v_fmac_f64_e32 v[6:7], v[6:7], v[14:15]
	v_mul_f64 v[14:15], v[10:11], s[20:21]
	v_mul_f64 v[18:19], v[12:13], v[14:15]
	v_fmac_f64_e32 v[8:9], v[12:13], v[14:15]
	v_mul_f64 v[12:13], v[10:11], s[42:43]
	v_mul_f64 v[14:15], v[12:13], v[16:17]
	v_fmac_f64_e32 v[6:7], v[12:13], v[16:17]
	v_mul_f64 v[12:13], v[10:11], s[44:45]
	v_mul_f64 v[16:17], v[12:13], v[18:19]
	v_fmac_f64_e32 v[8:9], v[12:13], v[18:19]
	v_mul_f64 v[12:13], v[10:11], s[46:47]
	v_mul_f64 v[18:19], v[12:13], v[14:15]
	v_fmac_f64_e32 v[6:7], v[12:13], v[14:15]
	v_mul_f64 v[12:13], v[10:11], s[48:49]
	v_mul_f64 v[14:15], v[12:13], v[16:17]
	v_fmac_f64_e32 v[8:9], v[12:13], v[16:17]
	v_mul_f64 v[12:13], v[10:11], s[50:51]
	v_mul_f64 v[16:17], v[12:13], v[18:19]
	v_fmac_f64_e32 v[6:7], v[12:13], v[18:19]
	v_mul_f64 v[12:13], v[10:11], s[52:53]
	s_mov_b32 s20, 0xf07c1f08
	v_mul_f64 v[18:19], v[12:13], v[14:15]
	v_fmac_f64_e32 v[8:9], v[12:13], v[14:15]
	v_mul_f64 v[12:13], v[10:11], s[54:55]
	s_mov_b32 s21, 0x3f7f07c1
	v_mul_f64 v[14:15], v[12:13], v[16:17]
	v_fmac_f64_e32 v[6:7], v[12:13], v[16:17]
	v_mul_f64 v[12:13], v[10:11], s[20:21]
	s_mov_b32 s20, 0x1a41a41a
	s_mov_b32 s21, 0x3f7a41a4
	v_writelane_b32 v255, s19, 15
	v_mul_f64 v[20:21], v[10:11], s[20:21]
	s_mov_b32 s20, 0x16816817
	s_mov_b32 s21, 0x3f768168
	v_readlane_b32 s28, v255, 16
	v_mul_f64 v[16:17], v[12:13], v[18:19]
	v_mul_f64 v[24:25], v[10:11], s[20:21]
	v_fmac_f64_e32 v[8:9], v[12:13], v[18:19]
	v_readlane_b32 s29, v255, 17
	s_mov_b32 s28, s44
	v_mul_f64 v[12:13], v[24:25], v[16:17]
	v_fmac_f64_e32 v[8:9], v[24:25], v[16:17]
	s_mov_b32 s19, s29
	v_mul_f64 v[16:17], v[10:11], s[28:29]
	s_mov_b32 s28, 0x1e1e1e1e
	s_mov_b32 s20, 0x13813814
	s_mov_b32 s29, 0x3f6e1e1e
	s_mov_b32 s21, 0x3f738138
	v_mul_f64 v[18:19], v[10:11], s[28:29]
	s_mov_b32 s28, 0xfd017f40
	v_mul_f64 v[22:23], v[20:21], v[14:15]
	v_mul_f64 v[26:27], v[10:11], s[20:21]
	v_fmac_f64_e32 v[6:7], v[20:21], v[14:15]
	s_mov_b32 s29, 0x3f67f405
	v_mul_f64 v[14:15], v[26:27], v[22:23]
	v_fmac_f64_e32 v[6:7], v[26:27], v[22:23]
	v_mul_f64 v[22:23], v[16:17], v[12:13]
	v_fmac_f64_e32 v[8:9], v[16:17], v[12:13]
	v_mul_f64 v[16:17], v[10:11], s[28:29]
	s_mov_b32 s28, 0x1ac5701b
	s_mov_b32 s29, 0x3f6ac570
	v_writelane_b32 v255, s18, 16
	v_mul_f64 v[20:21], v[18:19], v[14:15]
	v_fmac_f64_e32 v[6:7], v[18:19], v[14:15]
	v_mul_f64 v[18:19], v[10:11], s[28:29]
	s_mov_b32 s28, 0x308158ed
	v_writelane_b32 v255, s19, 17
	s_mov_b32 s29, 0x3f658ed2
	v_mul_f64 v[14:15], v[16:17], v[20:21]
	v_fmac_f64_e32 v[6:7], v[16:17], v[20:21]
	v_mul_f64 v[16:17], v[10:11], s[28:29]
	v_readlane_b32 s28, v255, 18
; __device__ __forceinline__ unsigned cvt_pk_bf16(float lo, float hi) { unsigned r; asm volatile("v_cvt_pk_bf16_f32 %0, %1, %2" : "=v"(r) : "v"(lo), "v"(hi)); return r; }
; #define WSYNC() asm volatile("s_waitcnt lgkmcnt(0)" ::: "memory")
; __device__ __forceinline__ void sincos_acc(float angf, float& s, float& c) {
;     const double x = (double)angf; const double k = rint(x * 0.15915494309189535); const double r = fma(-k, 6.283185307179586, x);
;     const double r2 = r * r; double ts = r, tc = 1.0, ss = r, cc = 1.0;
; #pragma unroll
;     for (int n = 1; n <= 14; ++n) { tc *= -r2 * (1.0 / (double)((2 * n - 1) * (2 * n))); cc += tc; ts *= -r2 * (1.0 / (double)((2 * n) * (2 * n + 1))); ss += ts; }
;     s = (float)ss; c = (float)cc;
; }
; __device__ __forceinline__ void s5_unit(LAS unsigned char* lw, int b, int g, const float* lam_re, const float* lam_im, const float* log_step, ...
;     ...
;     const float are = mag * cs, aim = mag * sn;
;     { const float den = lr * lr + li * li, nr = are - 1.0f, ni = aim; Fs[n] = (f32x2){(nr * lr + ni * li) / den, (ni * lr - nr * li) / den}; }
;     WSYNC();
;     bf16x8 Bf[8];
; #pragma unroll
;     for (int nb = 0; nb < 8; ++nb) {
;         const int ns = (nb & 3) * 16 + r; const f32x2 f = Fs[ns];
;         u32x4 wv = (u32x4){0u, 0u, 0u, 0u};
;         if (g4 < 2) {
;             const f32x4 br0 = *(const f32x4*)(b_re + (size_t)(g * 64 + ns) * 16 + g4 * 8), br1 = *(const f32x4*)(b_re + (size_t)(g * 64 + ns) * 16 + g4 * 8 + 4);
;             const f32x4 bi0 = *(const f32x4*)(b_im + (size_t)(g * 64 + ns) * 16 + g4 * 8), bi1 = *(const f32x4*)(b_im + (size_t)(g * 64 + ns) * 16 + g4 * 8 + 4);
;             f32x4 v0, v1;
;             if (nb < 4) { v0 = br0 * f.x - bi0 * f.y; v1 = br1 * f.x - bi1 * f.y; } else { v0 = bi0 * f.x + br0 * f.y; v1 = bi1 * f.x + br1 * f.y; }
;             wv.x = cvt_pk_bf16(v0[0], v0[1]); wv.y = cvt_pk_bf16(v0[2], v0[3]); wv.z = cvt_pk_bf16(v1[0], v1[1]); wv.w = cvt_pk_bf16(v1[2], v1[3]);
;         }
	v_readlane_b32 s29, v255, 19
	s_mov_b32 s21, s29
	v_mul_f64 v[12:13], v[18:19], v[22:23]
	v_fmac_f64_e32 v[8:9], v[18:19], v[22:23]
	v_mul_f64 v[18:19], v[10:11], s[20:21]
	s_mov_b32 s20, 0xb51f5e1a
	s_mov_b32 s21, 0x3f603091
	v_mul_f64 v[22:23], v[16:17], v[12:13]
	v_fmac_f64_e32 v[8:9], v[16:17], v[12:13]
	v_mul_f64 v[12:13], v[10:11], s[20:21]
	s_mov_b32 s20, 0x4046ed29
	s_mov_b32 s21, 0x3f61bb4a
	v_mul_f64 v[20:21], v[18:19], v[14:15]
	v_fmac_f64_e32 v[6:7], v[18:19], v[14:15]
	v_mul_f64 v[14:15], v[10:11], s[20:21]
	s_mov_b32 s20, 0x76b981db
	s_mov_b32 s21, 0x3f5dae60
	v_mul_f64 v[18:19], v[12:13], v[20:21]
	v_fmac_f64_e32 v[6:7], v[12:13], v[20:21]
	v_mul_f64 v[12:13], v[10:11], s[20:21]
	s_mov_b32 s20, 0xb4e81b4f
	s_mov_b32 s21, 0x3f5b4e81
	v_mul_f64 v[16:17], v[14:15], v[22:23]
	v_fmac_f64_e32 v[8:9], v[14:15], v[22:23]
	v_mul_f64 v[14:15], v[10:11], s[20:21]
	s_mov_b32 s20, 0xc201756d
	s_mov_b32 s21, 0x3f5756ca
	v_mul_f64 v[22:23], v[12:13], v[16:17]
	v_fmac_f64_e32 v[8:9], v[12:13], v[16:17]
	v_mul_f64 v[12:13], v[10:11], s[20:21]
	s_mov_b32 s20, 0x7f9b2ce6
	s_mov_b32 s21, 0x3f5934c6
	v_mul_f64 v[20:21], v[14:15], v[18:19]
	v_fmac_f64_e32 v[6:7], v[14:15], v[18:19]
	v_mul_f64 v[14:15], v[10:11], s[20:21]
	s_mov_b32 s20, 0x6b015ac0
	s_mov_b32 s21, 0x3f55ac05
	v_mul_f64 v[18:19], v[12:13], v[20:21]
	v_fmac_f64_e32 v[6:7], v[12:13], v[20:21]
	v_mul_f64 v[12:13], v[10:11], s[20:21]
	s_mov_b32 s20, 0x25d51f87
	s_mov_b32 s21, 0x3f542d66
	v_mul_f64 v[16:17], v[14:15], v[22:23]
	v_fmac_f64_e32 v[8:9], v[14:15], v[22:23]
	v_mul_f64 v[10:11], v[10:11], s[20:21]
	v_fmac_f64_e32 v[6:7], v[10:11], v[18:19]
	v_fmac_f64_e32 v[8:9], v[12:13], v[16:17]
	v_cvt_f32_f64_e32 v8, v[8:9]
	v_cvt_f32_f64_e32 v9, v[6:7]
	v_pk_mul_f32 v[90:91], v[4:5], v[8:9] op_sel_hi:[0,1]
	v_add_f32_e32 v6, -1.0, v90
	v_pk_mov_b32 v[10:11], v[90:91], v[90:91] op_sel:[1,0]
	v_mov_b32_e32 v8, v3
	v_mov_b32_e32 v11, v6
	v_pk_mul_f32 v[4:5], v[2:3], v[2:3]
	v_mov_b32_e32 v7, v91
	v_pk_mul_f32 v[8:9], v[8:9], v[10:11] op_sel_hi:[0,1]
	v_pk_fma_f32 v[10:11], v[2:3], v[6:7], v[8:9]
	v_pk_fma_f32 v[2:3], v[2:3], v[6:7], v[8:9] op_sel_hi:[0,1,1] neg_lo:[0,0,1] neg_hi:[0,0,1]
	v_pk_add_f32 v[4:5], v[4:5], v[4:5] op_sel:[0,1] op_sel_hi:[0,1]
	v_div_scale_f32 v2, s[20:21], v5, v5, v3
	v_rcp_f32_e32 v6, v2
	s_mov_b32 s19, s29
	v_writelane_b32 v255, s18, 18
	v_pk_mov_b32 v[92:93], v[90:91], v[90:91] op_sel:[1,0]
	v_fma_f32 v7, -v2, v6, 1.0
	v_fmac_f32_e32 v6, v7, v6
	v_div_scale_f32 v7, vcc, v3, v5, v3
	v_mul_f32_e32 v8, v7, v6
	v_fma_f32 v9, -v2, v8, v7
	v_fmac_f32_e32 v8, v9, v6
	v_fma_f32 v2, -v2, v8, v7
	v_div_fmas_f32 v2, v2, v6, v8
	v_div_fixup_f32 v3, v2, v5, v3
	v_div_scale_f32 v2, s[20:21], v4, v4, v10
	v_rcp_f32_e32 v5, v2
	v_writelane_b32 v255, s19, 19
	v_mov_b32_e32 v9, 0
	v_fma_f32 v6, -v2, v5, 1.0
	v_fmac_f32_e32 v5, v6, v5
	v_div_scale_f32 v6, vcc, v10, v4, v10
	v_mul_f32_e32 v7, v6, v5
	v_fma_f32 v8, -v2, v7, v6
	v_fmac_f32_e32 v7, v8, v5
	v_fma_f32 v2, -v2, v7, v6
	v_div_fmas_f32 v2, v2, v5, v7
	v_div_fixup_f32 v2, v2, v4, v10
	ds_write_b64 v135, v[2:3] offset:27648
	s_waitcnt lgkmcnt(0)
	v_or_b32_e32 v3, s18, v134
	v_mov_b32_e32 v2, 0
	v_lshlrev_b32_e32 v10, 6, v3
	v_mov_b32_e32 v6, 0
	v_mov_b32_e32 v7, 0
	v_mov_b32_e32 v8, 0
	s_and_saveexec_b64 s[20:21], s[2:3]
	s_cbranch_execz .LBB0_729
	v_mov_b32_e32 v11, v1
	v_lshl_add_u64 v[8:9], v[70:71], 0, v[10:11]
	global_load_dwordx4 v[4:7], v[8:9], off offset:16
	global_load_dwordx4 v[12:15], v[8:9], off
	v_lshl_add_u64 v[8:9], v[68:69], 0, v[10:11]
	global_load_dwordx4 v[16:19], v[8:9], off offset:16
	global_load_dwordx4 v[20:23], v[8:9], off
	ds_read_b64 v[8:9], v136 offset:27648
	s_waitcnt vmcnt(0) lgkmcnt(0)
	v_pk_mul_f32 v[6:7], v[8:9], v[6:7] op_sel:[1,0]
	s_waitcnt vmcnt(2)
	v_pk_mul_f32 v[12:13], v[8:9], v[12:13] op_sel:[1,0]
	v_pk_mul_f32 v[4:5], v[8:9], v[4:5] op_sel:[1,0]
	v_pk_mul_f32 v[14:15], v[8:9], v[14:15] op_sel:[1,0]
	s_waitcnt vmcnt(1)
	v_pk_fma_f32 v[18:19], v[8:9], v[18:19], v[6:7] op_sel_hi:[0,1,1] neg_lo:[0,0,1] neg_hi:[0,0,1]
	s_waitcnt vmcnt(0)
	v_pk_fma_f32 v[6:7], v[8:9], v[20:21], v[12:13] op_sel_hi:[0,1,1] neg_lo:[0,0,1] neg_hi:[0,0,1]
	v_pk_fma_f32 v[4:5], v[8:9], v[16:17], v[4:5] op_sel_hi:[0,1,1] neg_lo:[0,0,1] neg_hi:[0,0,1]
	v_pk_fma_f32 v[14:15], v[8:9], v[22:23], v[14:15] op_sel_hi:[0,1,1] neg_lo:[0,0,1] neg_hi:[0,0,1]
	v_cvt_pk_bf16_f32 v6, v6, v7
	v_cvt_pk_bf16_f32 v7, v14, v15
	v_cvt_pk_bf16_f32 v8, v4, v5
	v_cvt_pk_bf16_f32 v9, v18, v19

; __device__ __forceinline__ unsigned short f2bf(float f) { return (unsigned short)(cvt_pk_bf16(f, 0.f) & 0xffffu); }
; __device__ __forceinline__ void s5_unit(LAS unsigned char* lw, int b, int g, const float* lam_re, const float* lam_im, const float* log_step, ...
;     ...
;     bf16x8 CfT[4];
; #pragma unroll
;     for (int kk = 0; kk < 4; ++kk)
; #pragma unroll
;         for (int e = 0; e < 8; ++e) { const int kf_ = kk * 32 + g4 * 8 + e, n_ = kf_ >> 1;
;             const float v = (kf_ & 1) ? -c_im[(size_t)(g * 16 + r) * 64 + n_] : c_re[(size_t)(g * 16 + r) * 64 + n_];
;             CfT[kk][e] = (short)f2bf(v); }
;     const f32x4 dsk4 = *(const f32x4*)(d_skip + g * 16 + g4 * 4);
;     float hr = 0.f, hi = 0.f;
;     const bf16_t* zb = Z + (size_t)b * SEQ * ZW + g * 16;
;     bf16_t* ob = Z5 + (size_t)b * SEQ * 512 + g * 16;
;     const int g4c = g4 < 2 ? g4 : 0;
;     u32x4 vnext = *(const u32x4*)(zb + (size_t)(lane >> 1) * ZW + (lane & 1) * 8);
;     u32x4 an0 = *(const u32x4*)(zb + (size_t)r * ZW + g4c * 8), an1 = *(const u32x4*)(zb + (size_t)(16 + r) * ZW + g4c * 8);
.LBB0_743:
	s_or_b64 exec, exec, s[20:21]
	v_lshl_or_b32 v11, s26, 12, v145
	global_load_dword v226, v11, s[14:15]
	global_load_dword v227, v11, s[16:17]
	global_load_dword v228, v11, s[14:15] offset:4
	global_load_dword v229, v11, s[16:17] offset:4
	global_load_dword v230, v11, s[14:15] offset:8
	global_load_dword v231, v11, s[16:17] offset:8
	global_load_dword v232, v11, s[14:15] offset:12
	global_load_dword v233, v11, s[16:17] offset:12
	global_load_dword v234, v11, s[14:15] offset:64
	global_load_dword v235, v11, s[16:17] offset:64
	global_load_dword v236, v11, s[14:15] offset:68
	global_load_dword v237, v11, s[16:17] offset:68
	global_load_dword v238, v11, s[14:15] offset:72
	global_load_dword v239, v11, s[16:17] offset:72
	global_load_dword v240, v11, s[14:15] offset:76
	global_load_dword v241, v11, s[16:17] offset:76
	global_load_dword v242, v11, s[14:15] offset:128
	global_load_dword v243, v11, s[16:17] offset:128
	global_load_dword v244, v11, s[14:15] offset:132
	global_load_dword v245, v11, s[16:17] offset:132
	global_load_dword v246, v11, s[14:15] offset:136
	global_load_dword v247, v11, s[16:17] offset:136
	global_load_dword v248, v11, s[14:15] offset:140
	global_load_dword v249, v11, s[16:17] offset:140
	global_load_dword v250, v11, s[14:15] offset:192
	global_load_dword v251, v11, s[16:17] offset:192
	global_load_dword v212, v11, s[14:15] offset:196
	global_load_dword v213, v11, s[16:17] offset:196
	global_load_dword v214, v11, s[14:15] offset:200
	global_load_dword v215, v11, s[16:17] offset:200
	global_load_dword v216, v11, s[14:15] offset:204
	global_load_dword v217, v11, s[16:17] offset:204
	s_waitcnt vmcnt(0)
	v_cvt_pk_bf16_f32 v28, v226, v1
	s_and_b32 s21, s25, 31
	s_ashr_i32 s20, s1, 5
	s_lshl_b32 s27, s26, 4
	s_mov_b32 s19, s95
	s_lshl_b32 s94, s21, 5
	s_ashr_i32 s21, s20, 31
	s_mul_i32 s29, s20, 0xa00000
	v_lshlrev_b32_e32 v94, 1, v10
	s_mul_hi_i32 s28, s20, 0xa00000
	v_mov_b32_e32 v85, v1
	v_mov_b32_e32 v95, v1
	v_mov_b32_e32 v83, v1
	v_xor_b32_e32 v12, 0x80000000, v227
	v_cvt_pk_bf16_f32 v29, v12, v1
	v_cvt_pk_bf16_f32 v30, v228, v1
	v_xor_b32_e32 v12, 0x80000000, v229
	v_cvt_pk_bf16_f32 v31, v12, v1
	v_cvt_pk_bf16_f32 v32, v230, v1
	v_xor_b32_e32 v12, 0x80000000, v231
	v_cvt_pk_bf16_f32 v33, v12, v1
	v_cvt_pk_bf16_f32 v34, v232, v1
	v_xor_b32_e32 v12, 0x80000000, v233
	v_cvt_pk_bf16_f32 v35, v12, v1
	v_cvt_pk_bf16_f32 v36, v234, v1
	v_xor_b32_e32 v12, 0x80000000, v235
	v_cvt_pk_bf16_f32 v37, v12, v1
	v_cvt_pk_bf16_f32 v87, v236, v1
	v_xor_b32_e32 v12, 0x80000000, v237
	v_cvt_pk_bf16_f32 v89, v12, v1
	v_cvt_pk_bf16_f32 v96, v238, v1
	v_xor_b32_e32 v12, 0x80000000, v239
	v_cvt_pk_bf16_f32 v97, v12, v1
	v_cvt_pk_bf16_f32 v98, v240, v1
	v_xor_b32_e32 v12, 0x80000000, v241
	v_cvt_pk_bf16_f32 v99, v12, v1
	v_cvt_pk_bf16_f32 v100, v242, v1
	v_xor_b32_e32 v12, 0x80000000, v243
	v_cvt_pk_bf16_f32 v101, v12, v1
	v_cvt_pk_bf16_f32 v102, v244, v1
	v_xor_b32_e32 v12, 0x80000000, v245
	v_cvt_pk_bf16_f32 v103, v12, v1
	v_cvt_pk_bf16_f32 v104, v246, v1
	v_xor_b32_e32 v12, 0x80000000, v247
	v_cvt_pk_bf16_f32 v105, v12, v1
	v_cvt_pk_bf16_f32 v106, v248, v1
	v_xor_b32_e32 v12, 0x80000000, v249
	v_cvt_pk_bf16_f32 v107, v12, v1
	v_cvt_pk_bf16_f32 v108, v250, v1
	v_xor_b32_e32 v12, 0x80000000, v251
	v_cvt_pk_bf16_f32 v109, v12, v1
	v_cvt_pk_bf16_f32 v110, v212, v1
	v_xor_b32_e32 v12, 0x80000000, v213
	v_cvt_pk_bf16_f32 v111, v12, v1
	v_cvt_pk_bf16_f32 v112, v214, v1
	v_xor_b32_e32 v12, 0x80000000, v215
	v_cvt_pk_bf16_f32 v113, v12, v1
	v_cvt_pk_bf16_f32 v114, v216, v1
	v_lshl_add_u64 v[10:11], v[72:73], 0, s[18:19]
	s_add_u32 s18, s6, s29
	s_addc_u32 s19, s7, s28
	s_lshl_b32 s26, s26, 5
	s_add_u32 s18, s18, s26
	s_addc_u32 s19, s19, 0
	v_lshl_add_u64 v[18:19], s[18:19], 0, v[84:85]
	v_lshl_add_u64 v[12:13], s[18:19], 0, v[0:1]
	v_lshl_add_u64 v[18:19], v[18:19], 0, v[94:95]
	s_mov_b32 s18, 0x14000
	v_lshl_add_u64 v[20:21], v[12:13], 0, v[82:83]
	v_add_co_u32_e32 v26, vcc, s18, v18
	s_lshl_b64 s[18:19], s[20:21], 21
	s_nop 0
	v_addc_co_u32_e32 v27, vcc, 0, v19, vcc
	s_mov_b32 s21, 0x5040100
	v_or_b32_e32 v94, s29, v94
	v_mov_b32_e32 v95, s28
	v_xor_b32_e32 v12, 0x80000000, v217
	v_cvt_pk_bf16_f32 v83, v12, v1
	global_load_dwordx4 v[10:13], v[10:11], off
	s_nop 0
	global_load_dwordx4 v[62:65], v[20:21], off
	global_load_dwordx4 v[58:61], v[18:19], off
	global_load_dwordx4 v[54:57], v[26:27], off
	v_perm_b32 v18, v29, v28, s21
	v_perm_b32 v19, v31, v30, s21
	v_perm_b32 v20, v33, v32, s21
	v_perm_b32 v21, v35, v34, s21
	v_perm_b32 v26, v37, v36, s21
	v_perm_b32 v27, v89, v87, s21
	v_perm_b32 v28, v97, v96, s21
	v_perm_b32 v29, v99, v98, s21
	v_perm_b32 v30, v101, v100, s21
	v_perm_b32 v31, v103, v102, s21
	v_perm_b32 v32, v105, v104, s21
	v_perm_b32 v33, v107, v106, s21
	v_perm_b32 v34, v109, v108, s21
	v_perm_b32 v35, v111, v110, s21
	v_perm_b32 v36, v113, v112, s21
	v_perm_b32 v37, v83, v114, s21
	v_lshl_add_u64 v[102:103], v[76:77], 0, v[94:95]
	v_lshl_add_u64 v[104:105], v[78:79], 0, v[94:95]
	v_mad_i64_i32 v[106:107], s[20:21], s20, v223, v[80:81]
	v_mov_b32_e32 v94, 0
	v_mov_b32_e32 v96, v90
	v_mov_b32_e32 v97, v90
	v_mov_b32_e32 v98, v91
	v_mov_b32_e32 v99, v91
	v_lshl_add_u64 v[100:101], v[74:75], 0, s[18:19]
	s_mov_b32 s20, 63
	v_mov_b32_e32 v95, v94
